# seam before FFN2-down panel-local too (write-through conversion stores + counter) on top of the split seams
# baseline (speedup 1.0000x reference)
; #define LAS __attribute__((address_space(3)))
; #define SEAM(k) do { if (IN(k) && IN((k) + 1)) flat_barrier((unsigned*)(ws + WS_BAR + 65536), fgen, (unsigned)G); } while (0)
; #define SEAM(k) do { if (IN(k) && IN((k) + 1)) xcd_barrier(xbar); } while (0)
; __global__ void __launch_bounds__(NT, 2) hymba_fwd(Args args) {
;     ...
;         if (G == 256 && bx >= 128) p0_items(args, (LAS float*)(lds + wave * 16384), P0_GU2, P0_ALL, (bx - 128) * NWAVES + wave, 128 * NWAVES, lane);
;         else if (G != 256) p0_items(args, (LAS float*)(lds + wave * 16384), P0_GU2, P0_ALL, bx * NWAVES + wave, NGW, lane);
;     }
;     SEAM(11);
;     if (IN(12)) {
;         pg8::Gemm g{Hb, (const bf16*)(ws + WS_WD2), M, D, FF}; pg8::StaticOrder S; S.init(M, D, G, bx);
;         pg8::EpiFinal E{XB, args.out, ssq + 4 * M, (unsigned*)(ws + WS_CNT), args.in[I_FINN], 0.5f}; pg8::gemm_phase<pg8::EpiFinal, pg8::StaticOrder, false, true>(lds, g, S, E);
.LBB0_1356:
	s_cmp_gt_i32 s51, 12
	s_cselect_b64 s[4:5], -1, 0
	s_and_b64 s[6:7], s[14:15], s[4:5]
	s_andn2_b64 vcc, exec, s[6:7]
	s_cbranch_vccnz .LBB0_1410
	v_mov_b32_e32 v1, 0x23fc8
	ds_read_b32 v2, v1
	s_waitcnt lgkmcnt(0)
	v_readfirstlane_b32 s14, v2
	s_cmp_lg_u32 s14, 1
	s_cbranch_scc1 .Lgb9_full
	s_waitcnt vmcnt(0)
	s_barrier
	s_cmp_eq_u64 s[44:45], 0
	s_cbranch_scc1 .Lgb9_gend
	s_mov_b64 s[8:9], exec
	s_mov_b64 exec, s[44:45]
	v_mov_b32_e32 v1, 1
	s_cmp_lt_u32 s2, 128
	s_cbranch_scc1 .Lgb9_gnoconv
	v_mov_b32_e32 v0, 0x8b00
	global_atomic_add v0, v1, s[46:47]

; #define SEAM(k) do { if (IN(k) && IN((k) + 1)) flat_barrier((unsigned*)(ws + WS_BAR + 65536), fgen, (unsigned)G); } while (0)
; #define SEAM(k) do { if (IN(k) && IN((k) + 1)) xcd_barrier(xbar); } while (0)
; __global__ void __launch_bounds__(NT, 2) hymba_fwd(Args args) {
;     ...
;     SEAM(11);
;     if (IN(12)) {
;         pg8::Gemm g{Hb, (const bf16*)(ws + WS_WD2), M, D, FF}; pg8::StaticOrder S; S.init(M, D, G, bx);
;         pg8::EpiFinal E{XB, args.out, ssq + 4 * M, (unsigned*)(ws + WS_CNT), args.in[I_FINN], 0.5f}; pg8::gemm_phase<pg8::EpiFinal, pg8::StaticOrder, false, true>(lds, g, S, E);
.Lgb9_gpanel:
	v_mov_b32_e32 v0, 0x8b00
